# P15 carry-prefix remainder steps (ch%4): loads of all remaining steps issued together, one wait (was one serial round trip per step)
# baseline (speedup 1.0000x reference)
; __global__ void __launch_bounds__(512, 2) fwd_kernel(Params p) {
;     ...
; #pragma unroll 4
;                 for (int j = 0; j < ch; ++j) { const size_t ci = ((size_t)b * NCHUNK + j) * LRU_W + c; const f32x4 cp = *(const f32x4*)(carryP + ci), chh = *(const f32x4*)(carryH + ci);
;                     h[0] = cp.x * h[0] + chh.x; h[1] = cp.y * h[1] + chh.y; h[2] = cp.z * h[2] + chh.z; h[3] = cp.w * h[3] + chh.w; }
;                 const size_t row0 = (size_t)b * SEQ + (size_t)ch * CHL;
;                 u32x2 ca[8], cb[8], cg_[8], cx[8], na[8], nb[8], ng[8], nx_[8];
; #pragma unroll
;                 for (int j = 0; j < 8; ++j) { const size_t off = (row0 + j) * LRU_W + c; ca[j] = *(const u32x2*)(ascan + off); cb[j] = *(const u32x2*)(bscan + off); cg_[j] = *(const u32x2*)(gateb + off); cx[j] = *(const u32x2*)(xcb + off); }
.LBB0_1509:
	v_add_co_u32_e32 v76, vcc, 0xffe80000, v74
	s_nop 1
	v_addc_co_u32_e32 v77, vcc, -1, v75, vcc
	global_load_dwordx4 v[80:83], v[76:77], off
	global_load_dwordx4 v[84:87], v[74:75], off
	v_lshl_add_u64 v[74:75], v[74:75], 0, s[22:23]
	s_cmp_lt_u32 s39, 2
	s_cbranch_scc1 .Lp15_rem_go
	v_add_co_u32_e32 v76, vcc, 0xffe80000, v74
	s_nop 1
	v_addc_co_u32_e32 v77, vcc, -1, v75, vcc
	global_load_dwordx4 v[88:91], v[76:77], off
	global_load_dwordx4 v[92:95], v[74:75], off
	v_lshl_add_u64 v[74:75], v[74:75], 0, s[22:23]
	s_cmp_lt_u32 s39, 3
	s_cbranch_scc1 .Lp15_rem_go
	v_add_co_u32_e32 v76, vcc, 0xffe80000, v74
	s_nop 1
	v_addc_co_u32_e32 v77, vcc, -1, v75, vcc
	global_load_dwordx4 v[96:99], v[76:77], off
	global_load_dwordx4 v[100:103], v[74:75], off
	v_lshl_add_u64 v[74:75], v[74:75], 0, s[22:23]
.Lp15_rem_go:
	s_waitcnt vmcnt(0)
	v_pk_fma_f32 v[72:73], v[72:73], v[80:81], v[84:85]
	v_pk_fma_f32 v[78:79], v[78:79], v[82:83], v[86:87]
	s_cmp_lt_u32 s39, 2
	s_cbranch_scc1 .Lp15_rem_done
	v_pk_fma_f32 v[72:73], v[72:73], v[88:89], v[92:93]
	v_pk_fma_f32 v[78:79], v[78:79], v[90:91], v[94:95]
	s_cmp_lt_u32 s39, 3
	s_cbranch_scc1 .Lp15_rem_done
	v_pk_fma_f32 v[72:73], v[72:73], v[96:97], v[100:101]
	v_pk_fma_f32 v[78:79], v[78:79], v[98:99], v[102:103]
.Lp15_rem_done:
.LBB0_1510:
	s_ashr_i32 s47, s46, 31
	s_lshl_b64 s[38:39], s[44:45], 13
	s_lshl_b64 s[42:43], s[46:47], 6
	s_add_u32 s38, s38, s42
	s_addc_u32 s39, s39, s43
	s_mul_i32 s42, s39, 0x600
	v_mad_u64_u32 v[74:75], s[38:39], s38, v142, v[0:1]
	v_add_u32_e32 v75, s42, v75
	v_lshlrev_b64 v[74:75], 1, v[74:75]
	v_lshl_add_u64 v[76:77], s[16:17], 0, v[74:75]
	v_lshl_add_u64 v[80:81], s[12:13], 0, v[74:75]
	v_lshl_add_u64 v[82:83], s[10:11], 0, v[74:75]
	v_lshl_add_u64 v[84:85], s[14:15], 0, v[74:75]
	global_load_dwordx2 v[134:135], v[76:77], off
	global_load_dwordx2 v[136:137], v[80:81], off
	global_load_dwordx2 v[132:133], v[82:83], off
	global_load_dwordx2 v[138:139], v[84:85], off
	v_lshl_add_u64 v[76:77], v[74:75], 0, s[24:25]
	v_lshl_add_u64 v[80:81], s[16:17], 0, v[76:77]
	v_lshl_add_u64 v[82:83], s[12:13], 0, v[76:77]
	v_lshl_add_u64 v[84:85], s[10:11], 0, v[76:77]
	v_lshl_add_u64 v[76:77], s[14:15], 0, v[76:77]
	global_load_dwordx2 v[124:125], v[80:81], off
	global_load_dwordx2 v[128:129], v[82:83], off
	global_load_dwordx2 v[126:127], v[84:85], off
	global_load_dwordx2 v[130:131], v[76:77], off
	v_lshl_add_u64 v[76:77], v[74:75], 0, s[22:23]
	v_lshl_add_u64 v[80:81], s[16:17], 0, v[76:77]
	v_lshl_add_u64 v[82:83], s[12:13], 0, v[76:77]
	v_lshl_add_u64 v[84:85], s[10:11], 0, v[76:77]
	v_lshl_add_u64 v[76:77], s[14:15], 0, v[76:77]
	global_load_dwordx2 v[116:117], v[80:81], off
	global_load_dwordx2 v[120:121], v[82:83], off
	global_load_dwordx2 v[118:119], v[84:85], off
	global_load_dwordx2 v[122:123], v[76:77], off
	v_lshl_add_u64 v[76:77], v[74:75], 0, s[26:27]
	v_lshl_add_u64 v[80:81], s[16:17], 0, v[76:77]
	v_lshl_add_u64 v[82:83], s[12:13], 0, v[76:77]
	v_lshl_add_u64 v[84:85], s[10:11], 0, v[76:77]
	v_lshl_add_u64 v[76:77], s[14:15], 0, v[76:77]
	global_load_dwordx2 v[108:109], v[80:81], off
	global_load_dwordx2 v[112:113], v[82:83], off
	global_load_dwordx2 v[110:111], v[84:85], off
	global_load_dwordx2 v[114:115], v[76:77], off
	v_lshl_add_u64 v[76:77], v[74:75], 0, s[28:29]
	v_lshl_add_u64 v[80:81], s[16:17], 0, v[76:77]
	v_lshl_add_u64 v[82:83], s[12:13], 0, v[76:77]
	v_lshl_add_u64 v[84:85], s[10:11], 0, v[76:77]
	v_lshl_add_u64 v[76:77], s[14:15], 0, v[76:77]
	global_load_dwordx2 v[100:101], v[80:81], off
	global_load_dwordx2 v[104:105], v[82:83], off
	global_load_dwordx2 v[102:103], v[84:85], off
	global_load_dwordx2 v[106:107], v[76:77], off
	v_lshl_add_u64 v[76:77], v[74:75], 0, s[30:31]
	v_lshl_add_u64 v[80:81], s[16:17], 0, v[76:77]
	v_lshl_add_u64 v[82:83], s[12:13], 0, v[76:77]
	v_lshl_add_u64 v[84:85], s[10:11], 0, v[76:77]
	v_lshl_add_u64 v[76:77], s[14:15], 0, v[76:77]
	global_load_dwordx2 v[92:93], v[80:81], off
	global_load_dwordx2 v[96:97], v[82:83], off
	global_load_dwordx2 v[94:95], v[84:85], off
	global_load_dwordx2 v[98:99], v[76:77], off
	v_lshl_add_u64 v[76:77], v[74:75], 0, s[34:35]
	v_lshl_add_u64 v[80:81], s[16:17], 0, v[76:77]
	v_lshl_add_u64 v[82:83], s[12:13], 0, v[76:77]
	v_lshl_add_u64 v[88:89], s[10:11], 0, v[76:77]
	v_lshl_add_u64 v[76:77], s[14:15], 0, v[76:77]
	v_lshl_add_u64 v[74:75], v[74:75], 0, s[36:37]
	global_load_dwordx2 v[84:85], v[80:81], off
	global_load_dwordx2 v[86:87], v[82:83], off
	s_nop 0
	global_load_dwordx2 v[88:89], v[88:89], off
	s_nop 0
	global_load_dwordx2 v[90:91], v[76:77], off
	v_lshl_add_u64 v[76:77], s[16:17], 0, v[74:75]
	v_lshl_add_u64 v[80:81], s[12:13], 0, v[74:75]
	v_lshl_add_u64 v[82:83], s[10:11], 0, v[74:75]
	v_lshl_add_u64 v[144:145], s[14:15], 0, v[74:75]
	global_load_dwordx2 v[76:77], v[76:77], off
	s_nop 0
	global_load_dwordx2 v[80:81], v[80:81], off
	s_nop 0
	global_load_dwordx2 v[74:75], v[82:83], off
	s_nop 0
	global_load_dwordx2 v[82:83], v[144:145], off
	s_lshl_b64 s[38:39], s[44:45], 25
	s_lshl_b64 s[42:43], s[46:47], 18
	s_add_u32 s38, s38, s42
	s_addc_u32 s39, s39, s43
	s_add_u32 s42, s8, s38
	s_addc_u32 s43, s9, s39
	s_mul_i32 s39, s44, 0x1800000
	s_mul_i32 s45, s46, 0x30000
	s_mul_hi_i32 s38, s44, 0x1800000
	s_mul_hi_i32 s44, s46, 0x30000
	s_add_u32 s39, s39, s45
	s_addc_u32 s38, s38, s44
	s_add_u32 s44, s8, s39
	s_addc_u32 s45, s9, s38
	s_mov_b32 s38, -8
